# counted vmcnt waits per element in the batched prologue gain-transposes instead of one vmcnt(0) drain
# baseline (speedup 1.0000x reference)
; __device__ __forceinline__ void transpose_item(const float* W, int N, int k0, int n0, bf16_t* dst, int ldd, LAS float* scr, int lane, const float* gk = nullptr) {
;     ...
;     for (int i = 0; i < 32; ++i) { const int kk = 2 * i + (lane >> 5); scr[kk * 33 + (lane & 31)] = W[(size_t)(k0 + kk) * N + n0 + (lane & 31)] * (gk ? gk[k0 + kk] : 1.0f); }
;     asm volatile("s_waitcnt lgkmcnt(0)" ::: "memory");
; __global__ void __launch_bounds__(512, 2) fwd_mega(Args args) {
;     ...
;             if (r < I_UP) { const int kb = r / 176, nb = r % 176, n0 = 32 * nb; const int bj = n0 / DFF, ch = n0 % DFF; const int drow = (ch >> 7) * 256 + bj * 128 + (ch & 127);
;                 transpose_item(w_up + (size_t)l * DM * UPW, UPW, 64 * kb, n0, (bf16_t*)(wl + W_UP) + (size_t)drow * 1024, 1024, scr, lane, ln2 + (size_t)l * DM); continue; }
.Lgw1_nog:
	s_waitcnt vmcnt(31)
	v_mul_f32_e32 v96, v96, v128
	ds_write_b32 v21, v96
	s_waitcnt vmcnt(30)
	v_mul_f32_e32 v97, v97, v129
	ds_write_b32 v21, v97 offset:264
	s_waitcnt vmcnt(29)
	v_mul_f32_e32 v98, v98, v130
	ds_write_b32 v21, v98 offset:528
	s_waitcnt vmcnt(28)
	v_mul_f32_e32 v99, v99, v131
	ds_write_b32 v21, v99 offset:792
	s_waitcnt vmcnt(27)
	v_mul_f32_e32 v100, v100, v132
	ds_write_b32 v21, v100 offset:1056
	s_waitcnt vmcnt(26)
	v_mul_f32_e32 v101, v101, v133
	ds_write_b32 v21, v101 offset:1320
	s_waitcnt vmcnt(25)
	v_mul_f32_e32 v102, v102, v134
	ds_write_b32 v21, v102 offset:1584
	s_waitcnt vmcnt(24)
	v_mul_f32_e32 v103, v103, v135
	ds_write_b32 v21, v103 offset:1848
	s_waitcnt vmcnt(23)
	v_mul_f32_e32 v104, v104, v136
	ds_write_b32 v21, v104 offset:2112
	s_waitcnt vmcnt(22)
	v_mul_f32_e32 v105, v105, v137
	ds_write_b32 v21, v105 offset:2376
	s_waitcnt vmcnt(21)
	v_mul_f32_e32 v106, v106, v138
	ds_write_b32 v21, v106 offset:2640
	s_waitcnt vmcnt(20)
	v_mul_f32_e32 v107, v107, v139
	ds_write_b32 v21, v107 offset:2904
	s_waitcnt vmcnt(19)
	v_mul_f32_e32 v108, v108, v140
	ds_write_b32 v21, v108 offset:3168
	s_waitcnt vmcnt(18)
	v_mul_f32_e32 v109, v109, v141
	ds_write_b32 v21, v109 offset:3432
	s_waitcnt vmcnt(17)
	v_mul_f32_e32 v110, v110, v142
	ds_write_b32 v21, v110 offset:3696
	s_waitcnt vmcnt(16)
	v_mul_f32_e32 v111, v111, v143
	ds_write_b32 v21, v111 offset:3960
	s_waitcnt vmcnt(15)
	v_mul_f32_e32 v112, v112, v144
	ds_write_b32 v21, v112 offset:4224
	s_waitcnt vmcnt(14)
	v_mul_f32_e32 v113, v113, v145
	ds_write_b32 v21, v113 offset:4488
	s_waitcnt vmcnt(13)
	v_mul_f32_e32 v114, v114, v146
	ds_write_b32 v21, v114 offset:4752
	s_waitcnt vmcnt(12)
	v_mul_f32_e32 v115, v115, v147
	ds_write_b32 v21, v115 offset:5016
	s_waitcnt vmcnt(11)
	v_mul_f32_e32 v116, v116, v148
	ds_write_b32 v21, v116 offset:5280
	s_waitcnt vmcnt(10)
	v_mul_f32_e32 v117, v117, v149
	ds_write_b32 v21, v117 offset:5544
	s_waitcnt vmcnt(9)
	v_mul_f32_e32 v118, v118, v150
	ds_write_b32 v21, v118 offset:5808
	s_waitcnt vmcnt(8)
	v_mul_f32_e32 v119, v119, v151
	ds_write_b32 v21, v119 offset:6072
	s_waitcnt vmcnt(7)
	v_mul_f32_e32 v120, v120, v152
	ds_write_b32 v21, v120 offset:6336
	s_waitcnt vmcnt(6)
	v_mul_f32_e32 v121, v121, v153
	ds_write_b32 v21, v121 offset:6600
	s_waitcnt vmcnt(5)
	v_mul_f32_e32 v122, v122, v154
	ds_write_b32 v21, v122 offset:6864
	s_waitcnt vmcnt(4)
	v_mul_f32_e32 v123, v123, v155
	ds_write_b32 v21, v123 offset:7128
	s_waitcnt vmcnt(3)
	v_mul_f32_e32 v124, v124, v156
	ds_write_b32 v21, v124 offset:7392
	s_waitcnt vmcnt(2)
	v_mul_f32_e32 v125, v125, v157
	ds_write_b32 v21, v125 offset:7656
	s_waitcnt vmcnt(1)
	v_mul_f32_e32 v126, v126, v158
	ds_write_b32 v21, v126 offset:7920
	s_waitcnt vmcnt(0)
	v_mul_f32_e32 v127, v127, v159
	ds_write_b32 v21, v127 offset:8184
	v_add_u32_e32 v21, 0x2100, v21
	s_add_u32 s16, s16, 0x160000
	s_addc_u32 s17, s17, 0
	s_add_u32 s14, s14, 0x100
	s_addc_u32 s15, s15, 0
	s_branch .LBB0_37

; #define ln1 (karg(6))
; #define w_in (karg(7))
; __device__ __forceinline__ void transpose_item(const float* W, int N, int k0, int n0, bf16_t* dst, int ldd, LAS float* scr, int lane, const float* gk = nullptr) {
;     ...
;     for (int i = 0; i < 32; ++i) { const int kk = 2 * i + (lane >> 5); scr[kk * 33 + (lane & 31)] = W[(size_t)(k0 + kk) * N + n0 + (lane & 31)] * (gk ? gk[k0 + kk] : 1.0f); }
;     asm volatile("s_waitcnt lgkmcnt(0)" ::: "memory");
; __global__ void __launch_bounds__(512, 2) fwd_mega(Args args) {
;     ...
;             if (r < I_IN) { const int kb = r / 96, nb = r % 96, n0 = 32 * nb; const int drow = n0 < 1024 ? n0 : (n0 < 1536 ? 2560 + n0 - 1024 : (n0 < 2048 ? n0 - 512 : (n0 < 2560 ? 1536 + ((n0 - 2048) >> 7) * 256 + ((n0 - 2048) & 127) : 1536 + ((n0 - 2560) >> 7) * 256 + 128 + ((n0 - 2560) & 127))));
;                 transpose_item(w_in + (size_t)l * DM * PROJ, PROJ, 64 * kb, n0, (bf16_t*)(wl + W_IN) + (size_t)drow * 1024, 1024, scr, lane, ln1 + (size_t)l * DM); continue; }
.Lgw2_nog:
	s_waitcnt vmcnt(31)
	v_mul_f32_e32 v96, v96, v128
	ds_write_b32 v2, v96
	s_waitcnt vmcnt(30)
	v_mul_f32_e32 v97, v97, v129
	ds_write_b32 v2, v97 offset:264
	s_waitcnt vmcnt(29)
	v_mul_f32_e32 v98, v98, v130
	ds_write_b32 v2, v98 offset:528
	s_waitcnt vmcnt(28)
	v_mul_f32_e32 v99, v99, v131
	ds_write_b32 v2, v99 offset:792
	s_waitcnt vmcnt(27)
	v_mul_f32_e32 v100, v100, v132
	ds_write_b32 v2, v100 offset:1056
	s_waitcnt vmcnt(26)
	v_mul_f32_e32 v101, v101, v133
	ds_write_b32 v2, v101 offset:1320
	s_waitcnt vmcnt(25)
	v_mul_f32_e32 v102, v102, v134
	ds_write_b32 v2, v102 offset:1584
	s_waitcnt vmcnt(24)
	v_mul_f32_e32 v103, v103, v135
	ds_write_b32 v2, v103 offset:1848
	s_waitcnt vmcnt(23)
	v_mul_f32_e32 v104, v104, v136
	ds_write_b32 v2, v104 offset:2112
	s_waitcnt vmcnt(22)
	v_mul_f32_e32 v105, v105, v137
	ds_write_b32 v2, v105 offset:2376
	s_waitcnt vmcnt(21)
	v_mul_f32_e32 v106, v106, v138
	ds_write_b32 v2, v106 offset:2640
	s_waitcnt vmcnt(20)
	v_mul_f32_e32 v107, v107, v139
	ds_write_b32 v2, v107 offset:2904
	s_waitcnt vmcnt(19)
	v_mul_f32_e32 v108, v108, v140
	ds_write_b32 v2, v108 offset:3168
	s_waitcnt vmcnt(18)
	v_mul_f32_e32 v109, v109, v141
	ds_write_b32 v2, v109 offset:3432
	s_waitcnt vmcnt(17)
	v_mul_f32_e32 v110, v110, v142
	ds_write_b32 v2, v110 offset:3696
	s_waitcnt vmcnt(16)
	v_mul_f32_e32 v111, v111, v143
	ds_write_b32 v2, v111 offset:3960
	s_waitcnt vmcnt(15)
	v_mul_f32_e32 v112, v112, v144
	ds_write_b32 v2, v112 offset:4224
	s_waitcnt vmcnt(14)
	v_mul_f32_e32 v113, v113, v145
	ds_write_b32 v2, v113 offset:4488
	s_waitcnt vmcnt(13)
	v_mul_f32_e32 v114, v114, v146
	ds_write_b32 v2, v114 offset:4752
	s_waitcnt vmcnt(12)
	v_mul_f32_e32 v115, v115, v147
	ds_write_b32 v2, v115 offset:5016
	s_waitcnt vmcnt(11)
	v_mul_f32_e32 v116, v116, v148
	ds_write_b32 v2, v116 offset:5280
	s_waitcnt vmcnt(10)
	v_mul_f32_e32 v117, v117, v149
	ds_write_b32 v2, v117 offset:5544
	s_waitcnt vmcnt(9)
	v_mul_f32_e32 v118, v118, v150
	ds_write_b32 v2, v118 offset:5808
	s_waitcnt vmcnt(8)
	v_mul_f32_e32 v119, v119, v151
	ds_write_b32 v2, v119 offset:6072
	s_waitcnt vmcnt(7)
	v_mul_f32_e32 v120, v120, v152
	ds_write_b32 v2, v120 offset:6336
	s_waitcnt vmcnt(6)
	v_mul_f32_e32 v121, v121, v153
	ds_write_b32 v2, v121 offset:6600
	s_waitcnt vmcnt(5)
	v_mul_f32_e32 v122, v122, v154
	ds_write_b32 v2, v122 offset:6864
	s_waitcnt vmcnt(4)
	v_mul_f32_e32 v123, v123, v155
	ds_write_b32 v2, v123 offset:7128
	s_waitcnt vmcnt(3)
	v_mul_f32_e32 v124, v124, v156
	ds_write_b32 v2, v124 offset:7392
	s_waitcnt vmcnt(2)
	v_mul_f32_e32 v125, v125, v157
	ds_write_b32 v2, v125 offset:7656
	s_waitcnt vmcnt(1)
	v_mul_f32_e32 v126, v126, v158
	ds_write_b32 v2, v126 offset:7920
	s_waitcnt vmcnt(0)
	v_mul_f32_e32 v127, v127, v159
	ds_write_b32 v2, v127 offset:8184
	v_add_u32_e32 v2, 0x2100, v2
	s_add_u32 s18, s18, 0xc0000
	s_addc_u32 s19, s19, 0
	s_add_u32 s12, s12, 0x100
	s_addc_u32 s13, s13, 0
	s_branch .LBB0_9
